# v14: P4 merge epilogues with gate loads issued 8 (mid) / 4 (final) row-steps ahead behind counted waits, on top of v10
# baseline (speedup 1.0000x reference)
; __device__ __forceinline__ unsigned pk2(float lo, float hi) { f32x2 v = {lo, hi}; bf16x2_t b = __builtin_convertvector(v, bf16x2_t); return __builtin_bit_cast(unsigned, b); }
; __device__ __forceinline__ float bf_lo(unsigned u) { return __uint_as_float(u << 16); }
; __device__ __forceinline__ float bf_hi(unsigned u) { return __uint_as_float(u & 0xffff0000u); }
;     __device__ __forceinline__ void operator()(const AccT& acc, const Unit& u, int wr, int wc, int fr, int fq) const {
;         const size_t off0 = (size_t)(u.pm * BM + wr * 64 + fr) * 1024 + u.pn * BM + wc * 32 + 8 * fq;
; #pragma unroll
;         for (int ai = 0; ai < 2; ++ai)
; #pragma unroll
;             for (int m = 0; m < 4; ++m)
; #pragma unroll
;                 for (int bj = 0; bj < 2; ++bj) { const size_t off = off0 + (size_t)(ai * HALF + m * 16) * 1024 + bj * HALF;
;                     const u32x4 b = *(const u32x4*)(G2 + off);
;                     const f32x4 v0 = acc[ai][bj][m][0], v1 = acc[ai][bj][m][1];
;                     u32x4 w; w.x = pk2(v0[0] * bf_lo(b.x), v0[1] * bf_hi(b.x)); w.y = pk2(v0[2] * bf_lo(b.y), v0[3] * bf_hi(b.y));
;                     w.z = pk2(v1[0] * bf_lo(b.z), v1[1] * bf_hi(b.z)); w.w = pk2(v1[2] * bf_lo(b.w), v1[3] * bf_hi(b.w));
;                     *(u32x4*)(MIX + off) = w; }
.LBB0_471:
	s_cmp_lg_u32 s31, 0
	s_cselect_b64 s[28:29], -1, 0
	v_lshl_add_u32 v132, s30, 8, v186
	v_ashrrev_i32_e32 v133, 31, v132
	s_and_b64 vcc, exec, s[28:29]
	s_cbranch_vccz .LBB0_479
	s_lshl_b32 s21, s70, 8
	v_or_b32_e32 v222, s21, v174
	v_lshl_add_u32 v222, v132, 10, v222
	v_lshlrev_b32_e32 v222, 1, v222
	v_mov_b32_e32 v223, v222
	global_load_dwordx4 v[128:131], v222, s[12:13]
	global_load_dwordx4 v[132:135], v222, s[12:13] offset:256
	v_add_u32_e32 v222, 0x8000, v222
	global_load_dwordx4 v[136:139], v222, s[12:13]
	global_load_dwordx4 v[140:143], v222, s[12:13] offset:256
	s_waitcnt vmcnt(3)
	v_lshlrev_b32_e32 v218, 16, v128
	v_and_b32_e32 v219, 0xffff0000, v128
	v_pk_mul_f32 v[124:125], v[124:125], v[218:219]
	v_lshlrev_b32_e32 v218, 16, v129
	v_and_b32_e32 v219, 0xffff0000, v129
	v_pk_mul_f32 v[126:127], v[126:127], v[218:219]
	v_lshlrev_b32_e32 v220, 16, v130
	v_and_b32_e32 v221, 0xffff0000, v130
	v_pk_mul_f32 v[120:121], v[120:121], v[220:221]
	v_lshlrev_b32_e32 v220, 16, v131
	v_and_b32_e32 v221, 0xffff0000, v131
	v_add_u32_e32 v222, 0x8000, v222
	global_load_dwordx4 v[128:131], v222, s[12:13]
	v_pk_mul_f32 v[122:123], v[122:123], v[220:221]
	v_cvt_pk_bf16_f32 v124, v124, v125
	v_cvt_pk_bf16_f32 v125, v126, v127
	v_cvt_pk_bf16_f32 v126, v120, v121
	v_cvt_pk_bf16_f32 v127, v122, v123
	global_store_dwordx4 v223, v[124:127], s[14:15]
	s_waitcnt vmcnt(4)
	v_lshlrev_b32_e32 v218, 16, v132
	v_and_b32_e32 v219, 0xffff0000, v132
	v_pk_mul_f32 v[92:93], v[92:93], v[218:219]
	v_lshlrev_b32_e32 v218, 16, v133
	v_and_b32_e32 v219, 0xffff0000, v133
	v_pk_mul_f32 v[94:95], v[94:95], v[218:219]
	v_lshlrev_b32_e32 v220, 16, v134
	v_and_b32_e32 v221, 0xffff0000, v134
	v_pk_mul_f32 v[88:89], v[88:89], v[220:221]
	v_lshlrev_b32_e32 v220, 16, v135
	v_and_b32_e32 v221, 0xffff0000, v135
	global_load_dwordx4 v[132:135], v222, s[12:13] offset:256
	v_pk_mul_f32 v[90:91], v[90:91], v[220:221]
	v_cvt_pk_bf16_f32 v92, v92, v93
	v_cvt_pk_bf16_f32 v93, v94, v95
	v_cvt_pk_bf16_f32 v94, v88, v89
	v_cvt_pk_bf16_f32 v95, v90, v91
	global_store_dwordx4 v223, v[92:95], s[14:15] offset:256
	v_add_u32_e32 v223, 0x8000, v223
	s_waitcnt vmcnt(5)
	v_lshlrev_b32_e32 v218, 16, v136
	v_and_b32_e32 v219, 0xffff0000, v136
	v_pk_mul_f32 v[116:117], v[116:117], v[218:219]
	v_lshlrev_b32_e32 v218, 16, v137
	v_and_b32_e32 v219, 0xffff0000, v137
	v_pk_mul_f32 v[118:119], v[118:119], v[218:219]
	v_lshlrev_b32_e32 v220, 16, v138
	v_and_b32_e32 v221, 0xffff0000, v138
	v_pk_mul_f32 v[112:113], v[112:113], v[220:221]
	v_lshlrev_b32_e32 v220, 16, v139
	v_and_b32_e32 v221, 0xffff0000, v139
	v_add_u32_e32 v222, 0x8000, v222
	global_load_dwordx4 v[136:139], v222, s[12:13]
	v_pk_mul_f32 v[114:115], v[114:115], v[220:221]
	v_cvt_pk_bf16_f32 v116, v116, v117
	v_cvt_pk_bf16_f32 v117, v118, v119
	v_cvt_pk_bf16_f32 v118, v112, v113
	v_cvt_pk_bf16_f32 v119, v114, v115
	global_store_dwordx4 v223, v[116:119], s[14:15]
	s_waitcnt vmcnt(6)
	v_lshlrev_b32_e32 v218, 16, v140
	v_and_b32_e32 v219, 0xffff0000, v140
	v_pk_mul_f32 v[84:85], v[84:85], v[218:219]
	v_lshlrev_b32_e32 v218, 16, v141
	v_and_b32_e32 v219, 0xffff0000, v141
	v_pk_mul_f32 v[86:87], v[86:87], v[218:219]
	v_lshlrev_b32_e32 v220, 16, v142
	v_and_b32_e32 v221, 0xffff0000, v142
	v_pk_mul_f32 v[80:81], v[80:81], v[220:221]
	v_lshlrev_b32_e32 v220, 16, v143
	v_and_b32_e32 v221, 0xffff0000, v143
	global_load_dwordx4 v[140:143], v222, s[12:13] offset:256
	v_pk_mul_f32 v[82:83], v[82:83], v[220:221]
	v_cvt_pk_bf16_f32 v84, v84, v85
	v_cvt_pk_bf16_f32 v85, v86, v87
	v_cvt_pk_bf16_f32 v86, v80, v81
	v_cvt_pk_bf16_f32 v87, v82, v83
	global_store_dwordx4 v223, v[84:87], s[14:15] offset:256
	v_add_u32_e32 v223, 0x8000, v223
	s_waitcnt vmcnt(7)
	v_lshlrev_b32_e32 v218, 16, v128
	v_and_b32_e32 v219, 0xffff0000, v128
	v_pk_mul_f32 v[108:109], v[108:109], v[218:219]
	v_lshlrev_b32_e32 v218, 16, v129
	v_and_b32_e32 v219, 0xffff0000, v129
	v_pk_mul_f32 v[110:111], v[110:111], v[218:219]
	v_lshlrev_b32_e32 v220, 16, v130
	v_and_b32_e32 v221, 0xffff0000, v130
	v_pk_mul_f32 v[104:105], v[104:105], v[220:221]
	v_lshlrev_b32_e32 v220, 16, v131
	v_and_b32_e32 v221, 0xffff0000, v131
	v_add_u32_e32 v222, 0x28000, v222
	global_load_dwordx4 v[128:131], v222, s[12:13]
	v_pk_mul_f32 v[106:107], v[106:107], v[220:221]
	v_cvt_pk_bf16_f32 v108, v108, v109
	v_cvt_pk_bf16_f32 v109, v110, v111
	v_cvt_pk_bf16_f32 v110, v104, v105
	v_cvt_pk_bf16_f32 v111, v106, v107
	global_store_dwordx4 v223, v[108:111], s[14:15]
	s_waitcnt vmcnt(7)
	v_lshlrev_b32_e32 v218, 16, v132
	v_and_b32_e32 v219, 0xffff0000, v132
	v_pk_mul_f32 v[76:77], v[76:77], v[218:219]
	v_lshlrev_b32_e32 v218, 16, v133
	v_and_b32_e32 v219, 0xffff0000, v133
	v_pk_mul_f32 v[78:79], v[78:79], v[218:219]
	v_lshlrev_b32_e32 v220, 16, v134
	v_and_b32_e32 v221, 0xffff0000, v134
	v_pk_mul_f32 v[72:73], v[72:73], v[220:221]
	v_lshlrev_b32_e32 v220, 16, v135
	v_and_b32_e32 v221, 0xffff0000, v135
	global_load_dwordx4 v[132:135], v222, s[12:13] offset:256
	v_pk_mul_f32 v[74:75], v[74:75], v[220:221]
	v_cvt_pk_bf16_f32 v76, v76, v77
	v_cvt_pk_bf16_f32 v77, v78, v79
	v_cvt_pk_bf16_f32 v78, v72, v73
	v_cvt_pk_bf16_f32 v79, v74, v75
	global_store_dwordx4 v223, v[76:79], s[14:15] offset:256
	v_add_u32_e32 v223, 0x8000, v223
	s_waitcnt vmcnt(7)
; __device__ __forceinline__ unsigned pk2(float lo, float hi) { f32x2 v = {lo, hi}; bf16x2_t b = __builtin_convertvector(v, bf16x2_t); return __builtin_bit_cast(unsigned, b); }
; __device__ __forceinline__ float bf_lo(unsigned u) { return __uint_as_float(u << 16); }
; __device__ __forceinline__ float bf_hi(unsigned u) { return __uint_as_float(u & 0xffff0000u); }
;     __device__ __forceinline__ void operator()(const AccT& acc, const Unit& u, int wr, int wc, int fr, int fq) const {
;         const size_t off0 = (size_t)(u.pm * BM + wr * 64 + fr) * 1024 + u.pn * BM + wc * 32 + 8 * fq;
; #pragma unroll
;         for (int ai = 0; ai < 2; ++ai)
; #pragma unroll
;             for (int m = 0; m < 4; ++m)
; #pragma unroll
;                 for (int bj = 0; bj < 2; ++bj) { const size_t off = off0 + (size_t)(ai * HALF + m * 16) * 1024 + bj * HALF;
;                     const u32x4 b = *(const u32x4*)(G2 + off);
;                     const f32x4 v0 = acc[ai][bj][m][0], v1 = acc[ai][bj][m][1];
;                     u32x4 w; w.x = pk2(v0[0] * bf_lo(b.x), v0[1] * bf_hi(b.x)); w.y = pk2(v0[2] * bf_lo(b.y), v0[3] * bf_hi(b.y));
;                     w.z = pk2(v1[0] * bf_lo(b.z), v1[1] * bf_hi(b.z)); w.w = pk2(v1[2] * bf_lo(b.w), v1[3] * bf_hi(b.w));
;                     *(u32x4*)(MIX + off) = w; }
	v_lshlrev_b32_e32 v218, 16, v136
	v_and_b32_e32 v219, 0xffff0000, v136
	v_pk_mul_f32 v[100:101], v[100:101], v[218:219]
	v_lshlrev_b32_e32 v218, 16, v137
	v_and_b32_e32 v219, 0xffff0000, v137
	v_pk_mul_f32 v[102:103], v[102:103], v[218:219]
	v_lshlrev_b32_e32 v220, 16, v138
	v_and_b32_e32 v221, 0xffff0000, v138
	v_pk_mul_f32 v[96:97], v[96:97], v[220:221]
	v_lshlrev_b32_e32 v220, 16, v139
	v_and_b32_e32 v221, 0xffff0000, v139
	v_add_u32_e32 v222, 0x8000, v222
	global_load_dwordx4 v[136:139], v222, s[12:13]
	v_pk_mul_f32 v[98:99], v[98:99], v[220:221]
	v_cvt_pk_bf16_f32 v100, v100, v101
	v_cvt_pk_bf16_f32 v101, v102, v103
	v_cvt_pk_bf16_f32 v102, v96, v97
	v_cvt_pk_bf16_f32 v103, v98, v99
	global_store_dwordx4 v223, v[100:103], s[14:15]
	s_waitcnt vmcnt(7)
	v_lshlrev_b32_e32 v218, 16, v140
	v_and_b32_e32 v219, 0xffff0000, v140
	v_pk_mul_f32 v[68:69], v[68:69], v[218:219]
	v_lshlrev_b32_e32 v218, 16, v141
	v_and_b32_e32 v219, 0xffff0000, v141
	v_pk_mul_f32 v[70:71], v[70:71], v[218:219]
	v_lshlrev_b32_e32 v220, 16, v142
	v_and_b32_e32 v221, 0xffff0000, v142
	v_pk_mul_f32 v[64:65], v[64:65], v[220:221]
	v_lshlrev_b32_e32 v220, 16, v143
	v_and_b32_e32 v221, 0xffff0000, v143
	global_load_dwordx4 v[140:143], v222, s[12:13] offset:256
	v_pk_mul_f32 v[66:67], v[66:67], v[220:221]
	v_cvt_pk_bf16_f32 v68, v68, v69
	v_cvt_pk_bf16_f32 v69, v70, v71
	v_cvt_pk_bf16_f32 v70, v64, v65
	v_cvt_pk_bf16_f32 v71, v66, v67
	global_store_dwordx4 v223, v[68:71], s[14:15] offset:256
	v_add_u32_e32 v223, 0x28000, v223
	s_waitcnt vmcnt(7)
	v_lshlrev_b32_e32 v218, 16, v128
	v_and_b32_e32 v219, 0xffff0000, v128
	v_pk_mul_f32 v[60:61], v[60:61], v[218:219]
	v_lshlrev_b32_e32 v218, 16, v129
	v_and_b32_e32 v219, 0xffff0000, v129
	v_pk_mul_f32 v[62:63], v[62:63], v[218:219]
	v_lshlrev_b32_e32 v220, 16, v130
	v_and_b32_e32 v221, 0xffff0000, v130
	v_pk_mul_f32 v[56:57], v[56:57], v[220:221]
	v_lshlrev_b32_e32 v220, 16, v131
	v_and_b32_e32 v221, 0xffff0000, v131
	v_add_u32_e32 v222, 0x8000, v222
	global_load_dwordx4 v[128:131], v222, s[12:13]
	v_pk_mul_f32 v[58:59], v[58:59], v[220:221]
	v_cvt_pk_bf16_f32 v60, v60, v61
	v_cvt_pk_bf16_f32 v61, v62, v63
	v_cvt_pk_bf16_f32 v62, v56, v57
	v_cvt_pk_bf16_f32 v63, v58, v59
	global_store_dwordx4 v223, v[60:63], s[14:15]
	s_waitcnt vmcnt(7)
	v_lshlrev_b32_e32 v218, 16, v132
	v_and_b32_e32 v219, 0xffff0000, v132
	v_pk_mul_f32 v[28:29], v[28:29], v[218:219]
	v_lshlrev_b32_e32 v218, 16, v133
	v_and_b32_e32 v219, 0xffff0000, v133
	v_pk_mul_f32 v[30:31], v[30:31], v[218:219]
	v_lshlrev_b32_e32 v220, 16, v134
	v_and_b32_e32 v221, 0xffff0000, v134
	v_pk_mul_f32 v[24:25], v[24:25], v[220:221]
	v_lshlrev_b32_e32 v220, 16, v135
	v_and_b32_e32 v221, 0xffff0000, v135
	global_load_dwordx4 v[132:135], v222, s[12:13] offset:256
	v_pk_mul_f32 v[26:27], v[26:27], v[220:221]
	v_cvt_pk_bf16_f32 v28, v28, v29
	v_cvt_pk_bf16_f32 v29, v30, v31
	v_cvt_pk_bf16_f32 v30, v24, v25
	v_cvt_pk_bf16_f32 v31, v26, v27
	global_store_dwordx4 v223, v[28:31], s[14:15] offset:256
	v_add_u32_e32 v223, 0x8000, v223
	s_waitcnt vmcnt(7)
	v_lshlrev_b32_e32 v218, 16, v136
	v_and_b32_e32 v219, 0xffff0000, v136
	v_pk_mul_f32 v[52:53], v[52:53], v[218:219]
	v_lshlrev_b32_e32 v218, 16, v137
	v_and_b32_e32 v219, 0xffff0000, v137
	v_pk_mul_f32 v[54:55], v[54:55], v[218:219]
	v_lshlrev_b32_e32 v220, 16, v138
	v_and_b32_e32 v221, 0xffff0000, v138
	v_pk_mul_f32 v[48:49], v[48:49], v[220:221]
	v_lshlrev_b32_e32 v220, 16, v139
	v_and_b32_e32 v221, 0xffff0000, v139
	v_add_u32_e32 v222, 0x8000, v222
	global_load_dwordx4 v[136:139], v222, s[12:13]
	v_pk_mul_f32 v[50:51], v[50:51], v[220:221]
	v_cvt_pk_bf16_f32 v52, v52, v53
	v_cvt_pk_bf16_f32 v53, v54, v55
	v_cvt_pk_bf16_f32 v54, v48, v49
	v_cvt_pk_bf16_f32 v55, v50, v51
	global_store_dwordx4 v223, v[52:55], s[14:15]
	s_waitcnt vmcnt(7)
	v_lshlrev_b32_e32 v218, 16, v140
	v_and_b32_e32 v219, 0xffff0000, v140
	v_pk_mul_f32 v[20:21], v[20:21], v[218:219]
	v_lshlrev_b32_e32 v218, 16, v141
	v_and_b32_e32 v219, 0xffff0000, v141
	v_pk_mul_f32 v[22:23], v[22:23], v[218:219]
	v_lshlrev_b32_e32 v220, 16, v142
	v_and_b32_e32 v221, 0xffff0000, v142
	v_pk_mul_f32 v[16:17], v[16:17], v[220:221]
	v_lshlrev_b32_e32 v220, 16, v143
	v_and_b32_e32 v221, 0xffff0000, v143
	global_load_dwordx4 v[140:143], v222, s[12:13] offset:256
	v_pk_mul_f32 v[18:19], v[18:19], v[220:221]
	v_cvt_pk_bf16_f32 v20, v20, v21
	v_cvt_pk_bf16_f32 v21, v22, v23
	v_cvt_pk_bf16_f32 v22, v16, v17
	v_cvt_pk_bf16_f32 v23, v18, v19
	global_store_dwordx4 v223, v[20:23], s[14:15] offset:256
	v_add_u32_e32 v223, 0x8000, v223
	s_waitcnt vmcnt(7)
	v_lshlrev_b32_e32 v218, 16, v128
	v_and_b32_e32 v219, 0xffff0000, v128
	v_pk_mul_f32 v[44:45], v[44:45], v[218:219]
	v_lshlrev_b32_e32 v218, 16, v129
	v_and_b32_e32 v219, 0xffff0000, v129
	v_pk_mul_f32 v[46:47], v[46:47], v[218:219]
	v_lshlrev_b32_e32 v220, 16, v130
	v_and_b32_e32 v221, 0xffff0000, v130
	v_pk_mul_f32 v[40:41], v[40:41], v[220:221]
	v_lshlrev_b32_e32 v220, 16, v131
	v_and_b32_e32 v221, 0xffff0000, v131
	v_pk_mul_f32 v[42:43], v[42:43], v[220:221]
	v_cvt_pk_bf16_f32 v44, v44, v45
	v_cvt_pk_bf16_f32 v45, v46, v47
	v_cvt_pk_bf16_f32 v46, v40, v41
	v_cvt_pk_bf16_f32 v47, v42, v43
	global_store_dwordx4 v223, v[44:47], s[14:15]
	s_waitcnt vmcnt(6)
	v_lshlrev_b32_e32 v218, 16, v132
	v_and_b32_e32 v219, 0xffff0000, v132
	v_pk_mul_f32 v[12:13], v[12:13], v[218:219]
	v_lshlrev_b32_e32 v218, 16, v133
	v_and_b32_e32 v219, 0xffff0000, v133
	v_pk_mul_f32 v[14:15], v[14:15], v[218:219]
	v_lshlrev_b32_e32 v220, 16, v134
	v_and_b32_e32 v221, 0xffff0000, v134
	v_pk_mul_f32 v[8:9], v[8:9], v[220:221]
	v_lshlrev_b32_e32 v220, 16, v135
	v_and_b32_e32 v221, 0xffff0000, v135
	v_pk_mul_f32 v[10:11], v[10:11], v[220:221]
	v_cvt_pk_bf16_f32 v12, v12, v13
	v_cvt_pk_bf16_f32 v13, v14, v15
	v_cvt_pk_bf16_f32 v14, v8, v9
	v_cvt_pk_bf16_f32 v15, v10, v11
	global_store_dwordx4 v223, v[12:15], s[14:15] offset:256
	v_add_u32_e32 v223, 0x8000, v223
	s_waitcnt vmcnt(5)
; __device__ __forceinline__ unsigned pk2(float lo, float hi) { f32x2 v = {lo, hi}; bf16x2_t b = __builtin_convertvector(v, bf16x2_t); return __builtin_bit_cast(unsigned, b); }
; __device__ __forceinline__ float bf_lo(unsigned u) { return __uint_as_float(u << 16); }
; __device__ __forceinline__ float bf_hi(unsigned u) { return __uint_as_float(u & 0xffff0000u); }
;     __device__ __forceinline__ void mid(AccT& acc, const Unit& u, int wr, int wc, int fr, int fq) const {
;         const size_t off0 = (size_t)(u.pm * BM + wr * 64 + fr) * 1024 + u.pn * BM + wc * 32 + 8 * fq;
; #pragma unroll
;         for (int ai = 0; ai < 2; ++ai)
; #pragma unroll
;             for (int m = 0; m < 4; ++m)
; #pragma unroll
;                 for (int bj = 0; bj < 2; ++bj) { const size_t off = off0 + (size_t)(ai * HALF + m * 16) * 1024 + bj * HALF;
;                     const u32x4 a = *(const u32x4*)(G1 + off);
;                     const f32x4 r0 = (f32x4){bf_lo(a.x), bf_hi(a.x), bf_lo(a.y), bf_hi(a.y)}, r1 = (f32x4){bf_lo(a.z), bf_hi(a.z), bf_lo(a.w), bf_hi(a.w)};
;                     acc[ai][bj][m][0] = acc[ai][bj][m][0] * r0; acc[ai][bj][m][1] = acc[ai][bj][m][1] * r1; }
;     __device__ __forceinline__ void operator()(const AccT& acc, const Unit& u, int wr, int wc, int fr, int fq) const {
;         const size_t off0 = (size_t)(u.pm * BM + wr * 64 + fr) * 1024 + u.pn * BM + wc * 32 + 8 * fq;
; #pragma unroll
;         for (int ai = 0; ai < 2; ++ai)
; #pragma unroll
;             for (int m = 0; m < 4; ++m)
; #pragma unroll
;                 for (int bj = 0; bj < 2; ++bj) { const size_t off = off0 + (size_t)(ai * HALF + m * 16) * 1024 + bj * HALF;
;                     const u32x4 b = *(const u32x4*)(G2 + off);
;                     const f32x4 v0 = acc[ai][bj][m][0], v1 = acc[ai][bj][m][1];
;                     u32x4 w; w.x = pk2(v0[0] * bf_lo(b.x), v0[1] * bf_hi(b.x)); w.y = pk2(v0[2] * bf_lo(b.y), v0[3] * bf_hi(b.y));
;                     w.z = pk2(v1[0] * bf_lo(b.z), v1[1] * bf_hi(b.z)); w.w = pk2(v1[2] * bf_lo(b.w), v1[3] * bf_hi(b.w));
;                     *(u32x4*)(MIX + off) = w; }
	v_lshlrev_b32_e32 v218, 16, v136
	v_and_b32_e32 v219, 0xffff0000, v136
	v_pk_mul_f32 v[36:37], v[36:37], v[218:219]
	v_lshlrev_b32_e32 v218, 16, v137
	v_and_b32_e32 v219, 0xffff0000, v137
	v_pk_mul_f32 v[38:39], v[38:39], v[218:219]
	v_lshlrev_b32_e32 v220, 16, v138
	v_and_b32_e32 v221, 0xffff0000, v138
	v_pk_mul_f32 v[32:33], v[32:33], v[220:221]
	v_lshlrev_b32_e32 v220, 16, v139
	v_and_b32_e32 v221, 0xffff0000, v139
	v_pk_mul_f32 v[34:35], v[34:35], v[220:221]
	v_cvt_pk_bf16_f32 v36, v36, v37
	v_cvt_pk_bf16_f32 v37, v38, v39
	v_cvt_pk_bf16_f32 v38, v32, v33
	v_cvt_pk_bf16_f32 v39, v34, v35
	global_store_dwordx4 v223, v[36:39], s[14:15]
	s_waitcnt vmcnt(4)
	v_lshlrev_b32_e32 v218, 16, v140
	v_and_b32_e32 v219, 0xffff0000, v140
	v_pk_mul_f32 v[4:5], v[4:5], v[218:219]
	v_lshlrev_b32_e32 v218, 16, v141
	v_and_b32_e32 v219, 0xffff0000, v141
	v_pk_mul_f32 v[6:7], v[6:7], v[218:219]
	v_lshlrev_b32_e32 v220, 16, v142
	v_and_b32_e32 v221, 0xffff0000, v142
	v_pk_mul_f32 v[0:1], v[0:1], v[220:221]
	v_lshlrev_b32_e32 v220, 16, v143
	v_and_b32_e32 v221, 0xffff0000, v143
	v_pk_mul_f32 v[2:3], v[2:3], v[220:221]
	v_cvt_pk_bf16_f32 v4, v4, v5
	v_cvt_pk_bf16_f32 v5, v6, v7
	v_cvt_pk_bf16_f32 v6, v0, v1
	v_cvt_pk_bf16_f32 v7, v2, v3
	global_store_dwordx4 v223, v[4:7], s[14:15] offset:256
	s_cbranch_execnz .LBB0_474
.LBB0_473:
	s_lshl_b32 s30, s70, 8
	v_lshlrev_b64 v[128:129], 11, v[132:133]
	s_ashr_i32 s31, s30, 31
	v_lshl_add_u64 v[128:129], s[10:11], 0, v[128:129]
	v_lshl_add_u64 v[128:129], s[30:31], 1, v[128:129]
	v_lshl_add_u64 v[128:129], v[128:129], 0, s[6:7]
	v_lshl_add_u64 v[184:185], v[128:129], 0, v[172:173]
	v_subrev_u32_e32 v222, s10, v184
	global_load_dwordx4 v[128:131], v222, s[10:11]
	global_load_dwordx4 v[132:135], v222, s[10:11] offset:256
	v_add_u32_e32 v222, 0x8000, v222
	global_load_dwordx4 v[136:139], v222, s[10:11]
	global_load_dwordx4 v[140:143], v222, s[10:11] offset:256
	v_add_u32_e32 v222, 0x8000, v222
	global_load_dwordx4 v[144:147], v222, s[10:11]
	global_load_dwordx4 v[148:151], v222, s[10:11] offset:256
	v_add_u32_e32 v222, 0x8000, v222
	global_load_dwordx4 v[152:155], v222, s[10:11]
	global_load_dwordx4 v[156:159], v222, s[10:11] offset:256
	s_waitcnt vmcnt(7)
	v_lshlrev_b32_e32 v218, 16, v128
	v_and_b32_e32 v219, 0xffff0000, v128
	v_pk_mul_f32 v[124:125], v[124:125], v[218:219]
	v_lshlrev_b32_e32 v218, 16, v129
	v_and_b32_e32 v219, 0xffff0000, v129
	v_pk_mul_f32 v[126:127], v[126:127], v[218:219]
	v_lshlrev_b32_e32 v220, 16, v130
	v_and_b32_e32 v221, 0xffff0000, v130
	v_pk_mul_f32 v[120:121], v[120:121], v[220:221]
	v_lshlrev_b32_e32 v220, 16, v131
	v_and_b32_e32 v221, 0xffff0000, v131
	v_add_u32_e32 v222, 0x28000, v222
	global_load_dwordx4 v[128:131], v222, s[10:11]
	v_pk_mul_f32 v[122:123], v[122:123], v[220:221]
	s_waitcnt vmcnt(7)
	v_lshlrev_b32_e32 v218, 16, v132
	v_and_b32_e32 v219, 0xffff0000, v132
	v_pk_mul_f32 v[92:93], v[92:93], v[218:219]
	v_lshlrev_b32_e32 v218, 16, v133
	v_and_b32_e32 v219, 0xffff0000, v133
	v_pk_mul_f32 v[94:95], v[94:95], v[218:219]
	v_lshlrev_b32_e32 v220, 16, v134
	v_and_b32_e32 v221, 0xffff0000, v134
	v_pk_mul_f32 v[88:89], v[88:89], v[220:221]
	v_lshlrev_b32_e32 v220, 16, v135
	v_and_b32_e32 v221, 0xffff0000, v135
	global_load_dwordx4 v[132:135], v222, s[10:11] offset:256
	v_pk_mul_f32 v[90:91], v[90:91], v[220:221]
	s_waitcnt vmcnt(7)
	v_lshlrev_b32_e32 v218, 16, v136
	v_and_b32_e32 v219, 0xffff0000, v136
	v_pk_mul_f32 v[116:117], v[116:117], v[218:219]
	v_lshlrev_b32_e32 v218, 16, v137
	v_and_b32_e32 v219, 0xffff0000, v137
	v_pk_mul_f32 v[118:119], v[118:119], v[218:219]
	v_lshlrev_b32_e32 v220, 16, v138
	v_and_b32_e32 v221, 0xffff0000, v138
	v_pk_mul_f32 v[112:113], v[112:113], v[220:221]
	v_lshlrev_b32_e32 v220, 16, v139
	v_and_b32_e32 v221, 0xffff0000, v139
	v_add_u32_e32 v222, 0x8000, v222
	global_load_dwordx4 v[136:139], v222, s[10:11]
	v_pk_mul_f32 v[114:115], v[114:115], v[220:221]
	s_waitcnt vmcnt(7)
	v_lshlrev_b32_e32 v218, 16, v140
	v_and_b32_e32 v219, 0xffff0000, v140
	v_pk_mul_f32 v[84:85], v[84:85], v[218:219]
	v_lshlrev_b32_e32 v218, 16, v141
	v_and_b32_e32 v219, 0xffff0000, v141
	v_pk_mul_f32 v[86:87], v[86:87], v[218:219]
	v_lshlrev_b32_e32 v220, 16, v142
	v_and_b32_e32 v221, 0xffff0000, v142
	v_pk_mul_f32 v[80:81], v[80:81], v[220:221]
	v_lshlrev_b32_e32 v220, 16, v143
	v_and_b32_e32 v221, 0xffff0000, v143
	global_load_dwordx4 v[140:143], v222, s[10:11] offset:256
	v_pk_mul_f32 v[82:83], v[82:83], v[220:221]
	s_waitcnt vmcnt(7)
	v_lshlrev_b32_e32 v218, 16, v144
	v_and_b32_e32 v219, 0xffff0000, v144
	v_pk_mul_f32 v[108:109], v[108:109], v[218:219]
	v_lshlrev_b32_e32 v218, 16, v145
	v_and_b32_e32 v219, 0xffff0000, v145
	v_pk_mul_f32 v[110:111], v[110:111], v[218:219]
	v_lshlrev_b32_e32 v220, 16, v146
	v_and_b32_e32 v221, 0xffff0000, v146
	v_pk_mul_f32 v[104:105], v[104:105], v[220:221]
	v_lshlrev_b32_e32 v220, 16, v147
	v_and_b32_e32 v221, 0xffff0000, v147
	v_add_u32_e32 v222, 0x8000, v222
	global_load_dwordx4 v[144:147], v222, s[10:11]
	v_pk_mul_f32 v[106:107], v[106:107], v[220:221]
	s_waitcnt vmcnt(7)
; __device__ __forceinline__ float bf_lo(unsigned u) { return __uint_as_float(u << 16); }
; __device__ __forceinline__ float bf_hi(unsigned u) { return __uint_as_float(u & 0xffff0000u); }
;     __device__ __forceinline__ void mid(AccT& acc, const Unit& u, int wr, int wc, int fr, int fq) const {
;         const size_t off0 = (size_t)(u.pm * BM + wr * 64 + fr) * 1024 + u.pn * BM + wc * 32 + 8 * fq;
; #pragma unroll
;         for (int ai = 0; ai < 2; ++ai)
; #pragma unroll
;             for (int m = 0; m < 4; ++m)
; #pragma unroll
;                 for (int bj = 0; bj < 2; ++bj) { const size_t off = off0 + (size_t)(ai * HALF + m * 16) * 1024 + bj * HALF;
;                     const u32x4 a = *(const u32x4*)(G1 + off);
;                     const f32x4 r0 = (f32x4){bf_lo(a.x), bf_hi(a.x), bf_lo(a.y), bf_hi(a.y)}, r1 = (f32x4){bf_lo(a.z), bf_hi(a.z), bf_lo(a.w), bf_hi(a.w)};
;                     acc[ai][bj][m][0] = acc[ai][bj][m][0] * r0; acc[ai][bj][m][1] = acc[ai][bj][m][1] * r1; }
	v_lshlrev_b32_e32 v218, 16, v148
	v_and_b32_e32 v219, 0xffff0000, v148
	v_pk_mul_f32 v[76:77], v[76:77], v[218:219]
	v_lshlrev_b32_e32 v218, 16, v149
	v_and_b32_e32 v219, 0xffff0000, v149
	v_pk_mul_f32 v[78:79], v[78:79], v[218:219]
	v_lshlrev_b32_e32 v220, 16, v150
	v_and_b32_e32 v221, 0xffff0000, v150
	v_pk_mul_f32 v[72:73], v[72:73], v[220:221]
	v_lshlrev_b32_e32 v220, 16, v151
	v_and_b32_e32 v221, 0xffff0000, v151
	global_load_dwordx4 v[148:151], v222, s[10:11] offset:256
	v_pk_mul_f32 v[74:75], v[74:75], v[220:221]
	s_waitcnt vmcnt(7)
	v_lshlrev_b32_e32 v218, 16, v152
	v_and_b32_e32 v219, 0xffff0000, v152
	v_pk_mul_f32 v[100:101], v[100:101], v[218:219]
	v_lshlrev_b32_e32 v218, 16, v153
	v_and_b32_e32 v219, 0xffff0000, v153
	v_pk_mul_f32 v[102:103], v[102:103], v[218:219]
	v_lshlrev_b32_e32 v220, 16, v154
	v_and_b32_e32 v221, 0xffff0000, v154
	v_pk_mul_f32 v[96:97], v[96:97], v[220:221]
	v_lshlrev_b32_e32 v220, 16, v155
	v_and_b32_e32 v221, 0xffff0000, v155
	v_add_u32_e32 v222, 0x8000, v222
	global_load_dwordx4 v[152:155], v222, s[10:11]
	v_pk_mul_f32 v[98:99], v[98:99], v[220:221]
	s_waitcnt vmcnt(7)
	v_lshlrev_b32_e32 v218, 16, v156
	v_and_b32_e32 v219, 0xffff0000, v156
	v_pk_mul_f32 v[68:69], v[68:69], v[218:219]
	v_lshlrev_b32_e32 v218, 16, v157
	v_and_b32_e32 v219, 0xffff0000, v157
	v_pk_mul_f32 v[70:71], v[70:71], v[218:219]
	v_lshlrev_b32_e32 v220, 16, v158
	v_and_b32_e32 v221, 0xffff0000, v158
	v_pk_mul_f32 v[64:65], v[64:65], v[220:221]
	v_lshlrev_b32_e32 v220, 16, v159
	v_and_b32_e32 v221, 0xffff0000, v159
	global_load_dwordx4 v[156:159], v222, s[10:11] offset:256
	v_pk_mul_f32 v[66:67], v[66:67], v[220:221]
	s_waitcnt vmcnt(7)
	v_lshlrev_b32_e32 v218, 16, v128
	v_and_b32_e32 v219, 0xffff0000, v128
	v_pk_mul_f32 v[60:61], v[60:61], v[218:219]
	v_lshlrev_b32_e32 v218, 16, v129
	v_and_b32_e32 v219, 0xffff0000, v129
	v_pk_mul_f32 v[62:63], v[62:63], v[218:219]
	v_lshlrev_b32_e32 v220, 16, v130
	v_and_b32_e32 v221, 0xffff0000, v130
	v_pk_mul_f32 v[56:57], v[56:57], v[220:221]
	v_lshlrev_b32_e32 v220, 16, v131
	v_and_b32_e32 v221, 0xffff0000, v131
	v_pk_mul_f32 v[58:59], v[58:59], v[220:221]
	s_waitcnt vmcnt(6)
	v_lshlrev_b32_e32 v218, 16, v132
	v_and_b32_e32 v219, 0xffff0000, v132
	v_pk_mul_f32 v[28:29], v[28:29], v[218:219]
	v_lshlrev_b32_e32 v218, 16, v133
	v_and_b32_e32 v219, 0xffff0000, v133
	v_pk_mul_f32 v[30:31], v[30:31], v[218:219]
	v_lshlrev_b32_e32 v220, 16, v134
	v_and_b32_e32 v221, 0xffff0000, v134
	v_pk_mul_f32 v[24:25], v[24:25], v[220:221]
	v_lshlrev_b32_e32 v220, 16, v135
	v_and_b32_e32 v221, 0xffff0000, v135
	v_pk_mul_f32 v[26:27], v[26:27], v[220:221]
	s_waitcnt vmcnt(5)
	v_lshlrev_b32_e32 v218, 16, v136
	v_and_b32_e32 v219, 0xffff0000, v136
	v_pk_mul_f32 v[52:53], v[52:53], v[218:219]
	v_lshlrev_b32_e32 v218, 16, v137
	v_and_b32_e32 v219, 0xffff0000, v137
	v_pk_mul_f32 v[54:55], v[54:55], v[218:219]
	v_lshlrev_b32_e32 v220, 16, v138
	v_and_b32_e32 v221, 0xffff0000, v138
	v_pk_mul_f32 v[48:49], v[48:49], v[220:221]
	v_lshlrev_b32_e32 v220, 16, v139
	v_and_b32_e32 v221, 0xffff0000, v139
	v_pk_mul_f32 v[50:51], v[50:51], v[220:221]
	s_waitcnt vmcnt(4)
	v_lshlrev_b32_e32 v218, 16, v140
	v_and_b32_e32 v219, 0xffff0000, v140
	v_pk_mul_f32 v[20:21], v[20:21], v[218:219]
	v_lshlrev_b32_e32 v218, 16, v141
	v_and_b32_e32 v219, 0xffff0000, v141
	v_pk_mul_f32 v[22:23], v[22:23], v[218:219]
	v_lshlrev_b32_e32 v220, 16, v142
	v_and_b32_e32 v221, 0xffff0000, v142
	v_pk_mul_f32 v[16:17], v[16:17], v[220:221]
	v_lshlrev_b32_e32 v220, 16, v143
	v_and_b32_e32 v221, 0xffff0000, v143
	v_pk_mul_f32 v[18:19], v[18:19], v[220:221]
	s_waitcnt vmcnt(3)
	v_lshlrev_b32_e32 v218, 16, v144
	v_and_b32_e32 v219, 0xffff0000, v144
	v_pk_mul_f32 v[44:45], v[44:45], v[218:219]
	v_lshlrev_b32_e32 v218, 16, v145
	v_and_b32_e32 v219, 0xffff0000, v145
	v_pk_mul_f32 v[46:47], v[46:47], v[218:219]
	v_lshlrev_b32_e32 v220, 16, v146
	v_and_b32_e32 v221, 0xffff0000, v146
	v_pk_mul_f32 v[40:41], v[40:41], v[220:221]
	v_lshlrev_b32_e32 v220, 16, v147
	v_and_b32_e32 v221, 0xffff0000, v147
	v_pk_mul_f32 v[42:43], v[42:43], v[220:221]
	s_waitcnt vmcnt(2)
	v_lshlrev_b32_e32 v218, 16, v148
	v_and_b32_e32 v219, 0xffff0000, v148
	v_pk_mul_f32 v[12:13], v[12:13], v[218:219]
	v_lshlrev_b32_e32 v218, 16, v149
	v_and_b32_e32 v219, 0xffff0000, v149
	v_pk_mul_f32 v[14:15], v[14:15], v[218:219]
	v_lshlrev_b32_e32 v220, 16, v150
	v_and_b32_e32 v221, 0xffff0000, v150
	v_pk_mul_f32 v[8:9], v[8:9], v[220:221]
	v_lshlrev_b32_e32 v220, 16, v151
	v_and_b32_e32 v221, 0xffff0000, v151
	v_pk_mul_f32 v[10:11], v[10:11], v[220:221]
	s_waitcnt vmcnt(1)
	v_lshlrev_b32_e32 v218, 16, v152
	v_and_b32_e32 v219, 0xffff0000, v152
	v_pk_mul_f32 v[36:37], v[36:37], v[218:219]
	v_lshlrev_b32_e32 v218, 16, v153
	v_and_b32_e32 v219, 0xffff0000, v153
	v_pk_mul_f32 v[38:39], v[38:39], v[218:219]
	v_lshlrev_b32_e32 v220, 16, v154
	v_and_b32_e32 v221, 0xffff0000, v154
	v_pk_mul_f32 v[32:33], v[32:33], v[220:221]
	v_lshlrev_b32_e32 v220, 16, v155
	v_and_b32_e32 v221, 0xffff0000, v155
	v_pk_mul_f32 v[34:35], v[34:35], v[220:221]
	s_waitcnt vmcnt(0)
	v_lshlrev_b32_e32 v218, 16, v156
	v_and_b32_e32 v219, 0xffff0000, v156
	v_pk_mul_f32 v[4:5], v[4:5], v[218:219]
	v_lshlrev_b32_e32 v218, 16, v157
	v_and_b32_e32 v219, 0xffff0000, v157
	v_pk_mul_f32 v[6:7], v[6:7], v[218:219]
	v_lshlrev_b32_e32 v220, 16, v158
	v_and_b32_e32 v221, 0xffff0000, v158
	v_pk_mul_f32 v[0:1], v[0:1], v[220:221]
	v_lshlrev_b32_e32 v220, 16, v159
	v_and_b32_e32 v221, 0xffff0000, v159
	v_pk_mul_f32 v[2:3], v[2:3], v[220:221]
